# out-proj k-loop: MFMA-only waves prefetch 64 KB of the tile's residual rows into L2 two K-tiles before the LayerNorm epilogue; x->bf16 conversion loop unrolled x2
# baseline (speedup 1.0000x reference)
; DI unsigned pk2(float lo, float hi) { const f32x2 v = {lo, hi}; const bf16x2_t b = __builtin_convertvector(v, bf16x2_t); return __builtin_bit_cast(unsigned, b); }
; DI void prep_phase(const Params& p, char* lds) {
;     ...
;         auto conv = [&](const float* __restrict__ srcp, bf16_t* __restrict__ dstp, size_t n8) {
;             for (size_t I = (size_t)bid * NTHR + tid; I < n8; I += (size_t)nb * NTHR) {
;                 const int c8 = (int)(I & 3), row = (int)(I >> 2) & 127, kt = (int)(I >> 9) & 31, blk = (int)(I >> 14);
;                 const float* s = srcp + ((size_t)(blk * 128 + row)) * 1024 + kt * 32 + c8 * 8;
;                 const f32x4 a = *(const f32x4*)s, b = *(const f32x4*)(s + 4);
;                 *(u32x4*)(dstp + I * 8) = (u32x4){pk2(a[0], a[1]), pk2(a[2], a[3]), pk2(b[0], b[1]), pk2(b[2], b[3])};
;             }
.Lcv_loop:
	s_cmp_lt_u32 s15, 2
	s_cbranch_scc1 .Lcv_single
	v_lshrrev_b32_e32 v1, 2, v12
	v_lshrrev_b32_e32 v10, 7, v12
	v_and_b32_e32 v14, 0x7f, v1
	v_and_or_b32 v10, v10, s12, v14
	v_lshlrev_b32_e32 v10, 12, v10
	v_lshlrev_b32_e32 v16, 3, v12
	v_and_b32_e32 v16, 24, v16
	v_lshl_add_u64 v[14:15], s[52:53], 0, v[10:11]
	v_and_b32_e32 v10, 0xf80, v1
	v_lshl_add_u64 v[14:15], v[14:15], 0, v[10:11]
	v_lshlrev_b32_e32 v10, 2, v16
	v_lshl_add_u64 v[22:23], v[14:15], 0, v[10:11]
	global_load_dwordx4 v[14:17], v[22:23], off
	global_load_dwordx4 v[18:21], v[22:23], off offset:16
	v_lshl_add_u64 v[6:7], v[12:13], 4, s[22:23]
	v_add_u32_e32 v12, 0x20000, v12
	v_lshrrev_b32_e32 v1, 2, v12
	v_lshrrev_b32_e32 v10, 7, v12
	v_and_b32_e32 v216, 0x7f, v1
	v_and_or_b32 v10, v10, s12, v216
	v_lshlrev_b32_e32 v10, 12, v10
	v_lshlrev_b32_e32 v218, 3, v12
	v_and_b32_e32 v218, 24, v218
	v_lshl_add_u64 v[216:217], s[52:53], 0, v[10:11]
	v_and_b32_e32 v10, 0xf80, v1
	v_lshl_add_u64 v[216:217], v[216:217], 0, v[10:11]
	v_lshlrev_b32_e32 v10, 2, v218
	v_lshl_add_u64 v[224:225], v[216:217], 0, v[10:11]
	global_load_dwordx4 v[216:219], v[224:225], off
	global_load_dwordx4 v[220:223], v[224:225], off offset:16
	v_lshl_add_u64 v[8:9], v[12:13], 4, s[22:23]
	v_add_u32_e32 v12, 0x20000, v12
	s_waitcnt vmcnt(3)
	v_cvt_pk_bf16_f32 v14, v14, v15
	v_cvt_pk_bf16_f32 v15, v16, v17
	s_waitcnt vmcnt(2)
	v_cvt_pk_bf16_f32 v16, v18, v19
	v_cvt_pk_bf16_f32 v17, v20, v21
	s_waitcnt vmcnt(1)
	v_cvt_pk_bf16_f32 v216, v216, v217
	v_cvt_pk_bf16_f32 v217, v218, v219
	s_waitcnt vmcnt(0)
	v_cvt_pk_bf16_f32 v218, v220, v221
	v_cvt_pk_bf16_f32 v219, v222, v223
	global_store_dwordx4 v[6:7], v[14:17], off
	global_store_dwordx4 v[8:9], v[216:219], off
	s_sub_u32 s15, s15, 2
	s_cmp_lg_u32 s15, 0
	s_cbranch_scc1 .Lcv_loop
	s_branch .Lcv_next

; DI unsigned pk2(float lo, float hi) { const f32x2 v = {lo, hi}; const bf16x2_t b = __builtin_convertvector(v, bf16x2_t); return __builtin_bit_cast(unsigned, b); }
; DI void prep_phase(const Params& p, char* lds) {
;     ...
;         auto conv = [&](const float* __restrict__ srcp, bf16_t* __restrict__ dstp, size_t n8) {
;             for (size_t I = (size_t)bid * NTHR + tid; I < n8; I += (size_t)nb * NTHR) {
;                 const int c8 = (int)(I & 3), row = (int)(I >> 2) & 127, kt = (int)(I >> 9) & 31, blk = (int)(I >> 14);
;                 const float* s = srcp + ((size_t)(blk * 128 + row)) * 1024 + kt * 32 + c8 * 8;
;                 const f32x4 a = *(const f32x4*)s, b = *(const f32x4*)(s + 4);
;                 *(u32x4*)(dstp + I * 8) = (u32x4){pk2(a[0], a[1]), pk2(a[2], a[3]), pk2(b[0], b[1]), pk2(b[2], b[3])};
;             }
;         };
;         conv(p.x, WS_PTR(bf16_t, OFF_XB0), (size_t)T_TOK * DM / 8);
;         conv(p.mem, WS_PTR(bf16_t, OFF_MEMB), (size_t)4096 * DM / 8);
;     }
.Lcv_next:
	s_cmp_lt_u32 s6, 32
	s_cbranch_scc1 .Lcv_done
	s_mul_i32 s17, s13, 224
	s_add_u32 s17, s17, s6
	s_sub_u32 s17, s17, 32
	s_add_u32 s13, s13, 1
	s_cmp_ge_u32 s17, 992
	s_cbranch_scc1 .Lcv_done
	s_lshr_b32 s14, s17, 5
	s_and_b32 s16, s17, 31
	s_mov_b32 s15, 1
	s_branch .Lcv_seg

; DI void wait_count(unsigned* c, unsigned need) {
;     if (threadIdx.x == 0) {
;         while (__hip_atomic_load(c, __ATOMIC_RELAXED, __HIP_MEMORY_SCOPE_AGENT) < need) __builtin_amdgcn_s_sleep(1);
;         __builtin_amdgcn_fence(__ATOMIC_ACQUIRE, "agent");
;     }
;     __syncthreads();
.Lxb_follow:
.Lxb_poll:
	s_sleep 1
	global_load_dword v0, v24, s[10:11] sc1
	s_waitcnt vmcnt(0)
	v_cmp_gt_u32_e32 vcc, s2, v0
	s_cbranch_vccnz .Lxb_poll
	buffer_inv sc1
	s_waitcnt vmcnt(0)

; DI void unit_O(const Params& p, char* lds, int l, int tile, int glu_tiles, int tile_b) {
;     ...
;     const float* xres = (l == 0) ? p.x : WS_PTR(const float, OFF_X1);
;     const size_t r0 = (size_t)tile * 64;
;     char* XR = lds;
;     float* GB = (float*)(lds + 131072);
;     float* red = (float*)(lds + 139264);
;     const int xrot = (int)(((blockIdx.x >> 3) + (blockIdx.x & 7) * 4) & 31) * 4;
;     const bf16_t* xbres = WS_PTR(const bf16_t, OFF_XB1) + ((size_t)((tile >> 1) * 32) * 128 + (tile & 1) * 64) * 32;
.Lpo1_c_entry:
	v_subrev_u32_e32 v246, 0x100, v212
	s_cmp_lg_u64 s[10:11], 0
	s_cbranch_scc1 .Lpo1_pf_l1
	v_lshlrev_b32_e32 v246, 7, v246
	s_lshl_b32 s94, s34, 18
	s_add_u32 s96, s52, s94
	s_addc_u32 s97, s53, 0
	s_mov_b32 s91, 2
	s_mov_b32 s90, 15
	s_branch .Lpo1_pf_set
.Lpo1_pf_l1:
	v_lshrrev_b32_e32 v247, 5, v246
	v_and_b32_e32 v246, 31, v246
	v_lshlrev_b32_e32 v246, 7, v246
	v_lshl_or_b32 v246, v247, 13, v246
	s_lshr_b32 s94, s34, 1
	s_lshl_b32 s94, s94, 18
	s_and_b32 s95, s34, 1
	s_lshl_b32 s95, s95, 12
	s_add_u32 s94, s94, s95
	s_add_u32 s96, s56, s94
	s_addc_u32 s97, s57, 0
	s_mov_b32 s91, 2
	s_mov_b32 s90, 16

; DI f32x4 mfma16(bf16x8 a, bf16x8 b, f32x4 c) { return __builtin_amdgcn_mfma_f32_16x16x32_bf16(a, b, c, 0, 0, 0); }
; template <int N> DI void wait_vm() { asm volatile("s_waitcnt vmcnt(%0)" ::"n"(N) : "memory"); }
; DI void raw_barrier() { asm volatile("" ::: "memory"); __builtin_amdgcn_s_barrier(); asm volatile("" ::: "memory"); }
;     ...
;     auto compute = [&](int cb, bool do_issue, int ikt, int ib) {
;         const char* base = lds + cb * BUF;
;         bf16x8 af[MT], bfr[NT];
; #pragma unroll
;         for (int nt = 0; nt < NT; ++nt) {
;             const int br = BM + (nt / NTS) * (BN / NSEG) + wc * (NTS * 16) + (nt % NTS) * 16;
;             bfr[nt] = *(const bf16x8*)(base + (br + l15) * 64 + rsw);
;         }
; #pragma unroll
;         for (int mt = 0; mt < MT; ++mt) af[mt] = *(const bf16x8*)(base + (wr * WM + mt * 16 + l15) * 64 + rsw);
;         constexpr int TOT = MT * NT, PER = (TOT + NIT - 1) / NIT;
; #pragma unroll
;         for (int part = 0; part < NIT; ++part) {
; #pragma unroll
;             for (int q = 0; q < PER; ++q) {
;                 const int idx = part * PER + q;
;                 if (idx < TOT) {
;                     const int mt = idx / NT, nt = idx % NT;
;                     acc[mt][nt] = SWAP ? mfma16(bfr[nt], af[mt], acc[mt][nt]) : mfma16(af[mt], bfr[nt], acc[mt][nt]);
;                 }
;             }
;             __builtin_amdgcn_sched_barrier(0);
;             if (do_issue) issue_one(ikt, ib, part);
;             __builtin_amdgcn_sched_barrier(0);
;         }
;     };
;     __syncthreads();
; #pragma unroll
;     for (int d = 0; d < D; ++d) issue(d, d);
;     int cb = 0, ib = D;
;     for (int kt = 0; kt < KT; ++kt) {
;         if (D > 1 && kt + D - 1 < KT) wait_vm<(D - 1) * NIT>(); else wait_vm<0>();
;         raw_barrier();
;         compute(cb, kt + D < KT, kt + D, ib);
;         cb = (cb + 1 == NST) ? 0 : cb + 1;
;         ib = (ib + 1 == NST) ? 0 : ib + 1;
.Lpo1_c_loop:
	s_bitcmp1_b32 s9, 0
	s_cselect_b32 s46, 0, 0x11000
	v_add_u32_e32 v198, s46, v140
	v_add_u32_e32 v197, v198, v141
	v_add_u32_e32 v196, v198, v139
	s_waitcnt lgkmcnt(8)
	v_mfma_f32_16x16x32_bf16 v[98:101], v[142:145], v[146:149], v[98:101]
	s_waitcnt lgkmcnt(7)
	v_mfma_f32_16x16x32_bf16 v[94:97], v[150:153], v[146:149], v[94:97]
	s_waitcnt lgkmcnt(6)
	v_mfma_f32_16x16x32_bf16 v[90:93], v[158:161], v[146:149], v[90:93]
	s_waitcnt lgkmcnt(5)
	v_mfma_f32_16x16x32_bf16 v[86:89], v[162:165], v[146:149], v[86:89]
	s_waitcnt lgkmcnt(4)
	v_mfma_f32_16x16x32_bf16 v[82:85], v[166:169], v[146:149], v[82:85]
	s_waitcnt lgkmcnt(3)
	v_mfma_f32_16x16x32_bf16 v[78:81], v[170:173], v[146:149], v[78:81]
	s_waitcnt lgkmcnt(2)
	v_mfma_f32_16x16x32_bf16 v[74:77], v[174:177], v[146:149], v[74:77]
	s_waitcnt lgkmcnt(1)
	v_mfma_f32_16x16x32_bf16 v[70:73], v[178:181], v[146:149], v[70:73]
	s_waitcnt lgkmcnt(0)
	s_barrier
	ds_read_b128 v[146:149], v196
	s_add_u32 s94, s9, s91
	s_sub_u32 s94, s94, 30
	s_cmp_lt_u32 s94, s91
	s_cbranch_scc0 .Lpo1_pf_skip
	s_lshl_b32 s94, s94, s90
	s_add_u32 s94, s96, s94
	s_addc_u32 s95, s97, 0
	global_load_dword v247, v246, s[94:95]
.Lpo1_pf_skip:
	v_mfma_f32_16x16x32_bf16 v[126:129], v[142:145], v[154:157], v[126:129]
	v_mfma_f32_16x16x32_bf16 v[122:125], v[150:153], v[154:157], v[122:125]
	v_mfma_f32_16x16x32_bf16 v[118:121], v[158:161], v[154:157], v[118:121]
	v_mfma_f32_16x16x32_bf16 v[114:117], v[162:165], v[154:157], v[114:117]
	v_mfma_f32_16x16x32_bf16 v[110:113], v[166:169], v[154:157], v[110:113]
	v_mfma_f32_16x16x32_bf16 v[106:109], v[170:173], v[154:157], v[106:109]
	v_mfma_f32_16x16x32_bf16 v[102:105], v[174:177], v[154:157], v[102:105]
	v_mfma_f32_16x16x32_bf16 v[66:69], v[178:181], v[154:157], v[66:69]
	ds_read_b128 v[154:157], v196 offset:1024
	v_mfma_f32_16x16x32_bf16 v[34:37], v[142:145], v[182:185], v[34:37]
	v_mfma_f32_16x16x32_bf16 v[30:33], v[150:153], v[182:185], v[30:33]
	v_mfma_f32_16x16x32_bf16 v[26:29], v[158:161], v[182:185], v[26:29]
	v_mfma_f32_16x16x32_bf16 v[22:25], v[162:165], v[182:185], v[22:25]
	v_mfma_f32_16x16x32_bf16 v[18:21], v[166:169], v[182:185], v[18:21]
	v_mfma_f32_16x16x32_bf16 v[14:17], v[170:173], v[182:185], v[14:17]
	v_mfma_f32_16x16x32_bf16 v[10:13], v[174:177], v[182:185], v[10:13]
	v_mfma_f32_16x16x32_bf16 v[6:9], v[178:181], v[182:185], v[6:9]
	ds_read_b128 v[182:185], v196 offset:2048
	v_mfma_f32_16x16x32_bf16 v[62:65], v[142:145], v[186:189], v[62:65]
	ds_read_b128 v[142:145], v197 offset:4096
	v_mfma_f32_16x16x32_bf16 v[58:61], v[150:153], v[186:189], v[58:61]
	ds_read_b128 v[150:153], v197 offset:5120
	v_mfma_f32_16x16x32_bf16 v[54:57], v[158:161], v[186:189], v[54:57]
	ds_read_b128 v[158:161], v197 offset:6144
	v_mfma_f32_16x16x32_bf16 v[50:53], v[162:165], v[186:189], v[50:53]
	ds_read_b128 v[162:165], v197 offset:7168
	v_mfma_f32_16x16x32_bf16 v[46:49], v[166:169], v[186:189], v[46:49]
	ds_read_b128 v[166:169], v197 offset:8192
	v_mfma_f32_16x16x32_bf16 v[42:45], v[170:173], v[186:189], v[42:45]
	ds_read_b128 v[170:173], v197 offset:9216
	v_mfma_f32_16x16x32_bf16 v[38:41], v[174:177], v[186:189], v[38:41]
	ds_read_b128 v[174:177], v197 offset:10240
	v_mfma_f32_16x16x32_bf16 v[2:5], v[178:181], v[186:189], v[2:5]
	ds_read_b128 v[178:181], v197 offset:11264
	ds_read_b128 v[186:189], v196 offset:3072
	s_add_i32 s9, s9, 1
	s_cmp_lg_u32 s9, 32
	s_cbranch_scc1 .Lpo1_c_loop
	s_waitcnt lgkmcnt(8)
	v_mfma_f32_16x16x32_bf16 v[98:101], v[142:145], v[146:149], v[98:101]
	s_waitcnt lgkmcnt(7)
	v_mfma_f32_16x16x32_bf16 v[94:97], v[150:153], v[146:149], v[94:97]
	s_waitcnt lgkmcnt(6)
	v_mfma_f32_16x16x32_bf16 v[90:93], v[158:161], v[146:149], v[90:93]
	s_waitcnt lgkmcnt(5)
	v_mfma_f32_16x16x32_bf16 v[86:89], v[162:165], v[146:149], v[86:89]
	s_waitcnt lgkmcnt(4)
	v_mfma_f32_16x16x32_bf16 v[82:85], v[166:169], v[146:149], v[82:85]
	s_waitcnt lgkmcnt(3)
	v_mfma_f32_16x16x32_bf16 v[78:81], v[170:173], v[146:149], v[78:81]
	s_waitcnt lgkmcnt(2)
	v_mfma_f32_16x16x32_bf16 v[74:77], v[174:177], v[146:149], v[74:77]
	s_waitcnt lgkmcnt(1)
	v_mfma_f32_16x16x32_bf16 v[70:73], v[178:181], v[146:149], v[70:73]
	s_waitcnt lgkmcnt(0)
	v_mfma_f32_16x16x32_bf16 v[126:129], v[142:145], v[154:157], v[126:129]
	v_mfma_f32_16x16x32_bf16 v[122:125], v[150:153], v[154:157], v[122:125]
	v_mfma_f32_16x16x32_bf16 v[118:121], v[158:161], v[154:157], v[118:121]
	v_mfma_f32_16x16x32_bf16 v[114:117], v[162:165], v[154:157], v[114:117]
	v_mfma_f32_16x16x32_bf16 v[110:113], v[166:169], v[154:157], v[110:113]
	v_mfma_f32_16x16x32_bf16 v[106:109], v[170:173], v[154:157], v[106:109]
	v_mfma_f32_16x16x32_bf16 v[102:105], v[174:177], v[154:157], v[102:105]
	v_mfma_f32_16x16x32_bf16 v[66:69], v[178:181], v[154:157], v[66:69]
	v_mfma_f32_16x16x32_bf16 v[34:37], v[142:145], v[182:185], v[34:37]
	v_mfma_f32_16x16x32_bf16 v[30:33], v[150:153], v[182:185], v[30:33]
	v_mfma_f32_16x16x32_bf16 v[26:29], v[158:161], v[182:185], v[26:29]
	v_mfma_f32_16x16x32_bf16 v[22:25], v[162:165], v[182:185], v[22:25]
	v_mfma_f32_16x16x32_bf16 v[18:21], v[166:169], v[182:185], v[18:21]
	v_mfma_f32_16x16x32_bf16 v[14:17], v[170:173], v[182:185], v[14:17]
	v_mfma_f32_16x16x32_bf16 v[10:13], v[174:177], v[182:185], v[10:13]
	v_mfma_f32_16x16x32_bf16 v[6:9], v[178:181], v[182:185], v[6:9]
	v_mfma_f32_16x16x32_bf16 v[62:65], v[142:145], v[186:189], v[62:65]
	v_mfma_f32_16x16x32_bf16 v[58:61], v[150:153], v[186:189], v[58:61]
	v_mfma_f32_16x16x32_bf16 v[54:57], v[158:161], v[186:189], v[54:57]
	v_mfma_f32_16x16x32_bf16 v[50:53], v[162:165], v[186:189], v[50:53]
	v_mfma_f32_16x16x32_bf16 v[46:49], v[166:169], v[186:189], v[46:49]
	v_mfma_f32_16x16x32_bf16 v[42:45], v[170:173], v[186:189], v[42:45]
	v_mfma_f32_16x16x32_bf16 v[38:41], v[174:177], v[186:189], v[38:41]
	v_mfma_f32_16x16x32_bf16 v[2:5], v[178:181], v[186:189], v[2:5]

; DI void unit_O(const Params& p, char* lds, int l, int tile, int glu_tiles, int tile_b) {
;     ...
;     const float* xres = (l == 0) ? p.x : WS_PTR(const float, OFF_X1);
;     const size_t r0 = (size_t)tile * 64;
;     char* XR = lds;
;     float* GB = (float*)(lds + 131072);
;     float* red = (float*)(lds + 139264);
;     const int xrot = (int)(((blockIdx.x >> 3) + (blockIdx.x & 7) * 4) & 31) * 4;
;     const bf16_t* xbres = WS_PTR(const bf16_t, OFF_XB1) + ((size_t)((tile >> 1) * 32) * 128 + (tile & 1) * 64) * 32;
.Lpo2_c_entry:
	v_subrev_u32_e32 v246, 0x100, v212
	s_cmp_lg_u64 s[10:11], 0
	s_cbranch_scc1 .Lpo2_pf_l1
	v_lshlrev_b32_e32 v246, 7, v246
	s_lshl_b32 s94, s48, 18
	s_add_u32 s96, s52, s94
	s_addc_u32 s97, s53, 0
	s_mov_b32 s91, 2
	s_mov_b32 s90, 15
	s_branch .Lpo2_pf_set
.Lpo2_pf_l1:
	v_lshrrev_b32_e32 v247, 5, v246
	v_and_b32_e32 v246, 31, v246
	v_lshlrev_b32_e32 v246, 7, v246
	v_lshl_or_b32 v246, v247, 13, v246
	s_lshr_b32 s94, s48, 1
	s_lshl_b32 s94, s94, 18
	s_and_b32 s95, s48, 1
	s_lshl_b32 s95, s95, 12
	s_add_u32 s94, s94, s95
	s_add_u32 s96, s56, s94
	s_addc_u32 s97, s57, 0
	s_mov_b32 s91, 2
	s_mov_b32 s90, 16

; DI f32x4 mfma16(bf16x8 a, bf16x8 b, f32x4 c) { return __builtin_amdgcn_mfma_f32_16x16x32_bf16(a, b, c, 0, 0, 0); }
; template <int N> DI void wait_vm() { asm volatile("s_waitcnt vmcnt(%0)" ::"n"(N) : "memory"); }
; DI void raw_barrier() { asm volatile("" ::: "memory"); __builtin_amdgcn_s_barrier(); asm volatile("" ::: "memory"); }
;     ...
;     auto compute = [&](int cb, bool do_issue, int ikt, int ib) {
;         const char* base = lds + cb * BUF;
;         bf16x8 af[MT], bfr[NT];
; #pragma unroll
;         for (int nt = 0; nt < NT; ++nt) {
;             const int br = BM + (nt / NTS) * (BN / NSEG) + wc * (NTS * 16) + (nt % NTS) * 16;
;             bfr[nt] = *(const bf16x8*)(base + (br + l15) * 64 + rsw);
;         }
; #pragma unroll
;         for (int mt = 0; mt < MT; ++mt) af[mt] = *(const bf16x8*)(base + (wr * WM + mt * 16 + l15) * 64 + rsw);
;         constexpr int TOT = MT * NT, PER = (TOT + NIT - 1) / NIT;
; #pragma unroll
;         for (int part = 0; part < NIT; ++part) {
; #pragma unroll
;             for (int q = 0; q < PER; ++q) {
;                 const int idx = part * PER + q;
;                 if (idx < TOT) {
;                     const int mt = idx / NT, nt = idx % NT;
;                     acc[mt][nt] = SWAP ? mfma16(bfr[nt], af[mt], acc[mt][nt]) : mfma16(af[mt], bfr[nt], acc[mt][nt]);
;                 }
;             }
;             __builtin_amdgcn_sched_barrier(0);
;             if (do_issue) issue_one(ikt, ib, part);
;             __builtin_amdgcn_sched_barrier(0);
;         }
;     };
;     __syncthreads();
; #pragma unroll
;     for (int d = 0; d < D; ++d) issue(d, d);
;     int cb = 0, ib = D;
;     for (int kt = 0; kt < KT; ++kt) {
;         if (D > 1 && kt + D - 1 < KT) wait_vm<(D - 1) * NIT>(); else wait_vm<0>();
;         raw_barrier();
;         compute(cb, kt + D < KT, kt + D, ib);
;         cb = (cb + 1 == NST) ? 0 : cb + 1;
;         ib = (ib + 1 == NST) ? 0 : ib + 1;
.Lpo2_c_loop:
	s_bitcmp1_b32 s29, 0
	s_cselect_b32 s46, 0, 0x11000
	v_add_u32_e32 v198, s46, v140
	v_add_u32_e32 v197, v198, v141
	v_add_u32_e32 v196, v198, v139
	s_waitcnt lgkmcnt(8)
	v_mfma_f32_16x16x32_bf16 v[98:101], v[142:145], v[146:149], v[98:101]
	s_waitcnt lgkmcnt(7)
	v_mfma_f32_16x16x32_bf16 v[94:97], v[150:153], v[146:149], v[94:97]
	s_waitcnt lgkmcnt(6)
	v_mfma_f32_16x16x32_bf16 v[90:93], v[158:161], v[146:149], v[90:93]
	s_waitcnt lgkmcnt(5)
	v_mfma_f32_16x16x32_bf16 v[86:89], v[162:165], v[146:149], v[86:89]
	s_waitcnt lgkmcnt(4)
	v_mfma_f32_16x16x32_bf16 v[82:85], v[166:169], v[146:149], v[82:85]
	s_waitcnt lgkmcnt(3)
	v_mfma_f32_16x16x32_bf16 v[78:81], v[170:173], v[146:149], v[78:81]
	s_waitcnt lgkmcnt(2)
	v_mfma_f32_16x16x32_bf16 v[74:77], v[174:177], v[146:149], v[74:77]
	s_waitcnt lgkmcnt(1)
	v_mfma_f32_16x16x32_bf16 v[70:73], v[178:181], v[146:149], v[70:73]
	s_waitcnt lgkmcnt(0)
	s_barrier
	ds_read_b128 v[146:149], v196
	s_add_u32 s94, s29, s91
	s_sub_u32 s94, s94, 30
	s_cmp_lt_u32 s94, s91
	s_cbranch_scc0 .Lpo2_pf_skip
	s_lshl_b32 s94, s94, s90
	s_add_u32 s94, s96, s94
	s_addc_u32 s95, s97, 0
	global_load_dword v247, v246, s[94:95]
.Lpo2_pf_skip:
	v_mfma_f32_16x16x32_bf16 v[126:129], v[142:145], v[154:157], v[126:129]
	v_mfma_f32_16x16x32_bf16 v[122:125], v[150:153], v[154:157], v[122:125]
	v_mfma_f32_16x16x32_bf16 v[118:121], v[158:161], v[154:157], v[118:121]
	v_mfma_f32_16x16x32_bf16 v[114:117], v[162:165], v[154:157], v[114:117]
	v_mfma_f32_16x16x32_bf16 v[110:113], v[166:169], v[154:157], v[110:113]
	v_mfma_f32_16x16x32_bf16 v[106:109], v[170:173], v[154:157], v[106:109]
	v_mfma_f32_16x16x32_bf16 v[102:105], v[174:177], v[154:157], v[102:105]
	v_mfma_f32_16x16x32_bf16 v[66:69], v[178:181], v[154:157], v[66:69]
	ds_read_b128 v[154:157], v196 offset:1024
	v_mfma_f32_16x16x32_bf16 v[34:37], v[142:145], v[182:185], v[34:37]
	v_mfma_f32_16x16x32_bf16 v[30:33], v[150:153], v[182:185], v[30:33]
	v_mfma_f32_16x16x32_bf16 v[26:29], v[158:161], v[182:185], v[26:29]
	v_mfma_f32_16x16x32_bf16 v[22:25], v[162:165], v[182:185], v[22:25]
	v_mfma_f32_16x16x32_bf16 v[18:21], v[166:169], v[182:185], v[18:21]
	v_mfma_f32_16x16x32_bf16 v[14:17], v[170:173], v[182:185], v[14:17]
	v_mfma_f32_16x16x32_bf16 v[10:13], v[174:177], v[182:185], v[10:13]
	v_mfma_f32_16x16x32_bf16 v[6:9], v[178:181], v[182:185], v[6:9]
	ds_read_b128 v[182:185], v196 offset:2048
	v_mfma_f32_16x16x32_bf16 v[62:65], v[142:145], v[186:189], v[62:65]
	ds_read_b128 v[142:145], v197 offset:4096
	v_mfma_f32_16x16x32_bf16 v[58:61], v[150:153], v[186:189], v[58:61]
	ds_read_b128 v[150:153], v197 offset:5120
	v_mfma_f32_16x16x32_bf16 v[54:57], v[158:161], v[186:189], v[54:57]
	ds_read_b128 v[158:161], v197 offset:6144
	v_mfma_f32_16x16x32_bf16 v[50:53], v[162:165], v[186:189], v[50:53]
	ds_read_b128 v[162:165], v197 offset:7168
	v_mfma_f32_16x16x32_bf16 v[46:49], v[166:169], v[186:189], v[46:49]
	ds_read_b128 v[166:169], v197 offset:8192
	v_mfma_f32_16x16x32_bf16 v[42:45], v[170:173], v[186:189], v[42:45]
	ds_read_b128 v[170:173], v197 offset:9216
	v_mfma_f32_16x16x32_bf16 v[38:41], v[174:177], v[186:189], v[38:41]
	ds_read_b128 v[174:177], v197 offset:10240
	v_mfma_f32_16x16x32_bf16 v[2:5], v[178:181], v[186:189], v[2:5]
	ds_read_b128 v[178:181], v197 offset:11264
	ds_read_b128 v[186:189], v196 offset:3072
	s_add_i32 s29, s29, 1
	s_cmp_lg_u32 s29, 32
	s_cbranch_scc1 .Lpo2_c_loop
	s_waitcnt lgkmcnt(8)
	v_mfma_f32_16x16x32_bf16 v[98:101], v[142:145], v[146:149], v[98:101]
	s_waitcnt lgkmcnt(7)
	v_mfma_f32_16x16x32_bf16 v[94:97], v[150:153], v[146:149], v[94:97]
	s_waitcnt lgkmcnt(6)
	v_mfma_f32_16x16x32_bf16 v[90:93], v[158:161], v[146:149], v[90:93]
	s_waitcnt lgkmcnt(5)
	v_mfma_f32_16x16x32_bf16 v[86:89], v[162:165], v[146:149], v[86:89]
	s_waitcnt lgkmcnt(4)
	v_mfma_f32_16x16x32_bf16 v[82:85], v[166:169], v[146:149], v[82:85]
	s_waitcnt lgkmcnt(3)
	v_mfma_f32_16x16x32_bf16 v[78:81], v[170:173], v[146:149], v[78:81]
	s_waitcnt lgkmcnt(2)
	v_mfma_f32_16x16x32_bf16 v[74:77], v[174:177], v[146:149], v[74:77]
	s_waitcnt lgkmcnt(1)
	v_mfma_f32_16x16x32_bf16 v[70:73], v[178:181], v[146:149], v[70:73]
	s_waitcnt lgkmcnt(0)
	v_mfma_f32_16x16x32_bf16 v[126:129], v[142:145], v[154:157], v[126:129]
	v_mfma_f32_16x16x32_bf16 v[122:125], v[150:153], v[154:157], v[122:125]
	v_mfma_f32_16x16x32_bf16 v[118:121], v[158:161], v[154:157], v[118:121]
	v_mfma_f32_16x16x32_bf16 v[114:117], v[162:165], v[154:157], v[114:117]
	v_mfma_f32_16x16x32_bf16 v[110:113], v[166:169], v[154:157], v[110:113]
	v_mfma_f32_16x16x32_bf16 v[106:109], v[170:173], v[154:157], v[106:109]
	v_mfma_f32_16x16x32_bf16 v[102:105], v[174:177], v[154:157], v[102:105]
	v_mfma_f32_16x16x32_bf16 v[66:69], v[178:181], v[154:157], v[66:69]
	v_mfma_f32_16x16x32_bf16 v[34:37], v[142:145], v[182:185], v[34:37]
	v_mfma_f32_16x16x32_bf16 v[30:33], v[150:153], v[182:185], v[30:33]
	v_mfma_f32_16x16x32_bf16 v[26:29], v[158:161], v[182:185], v[26:29]
	v_mfma_f32_16x16x32_bf16 v[22:25], v[162:165], v[182:185], v[22:25]
	v_mfma_f32_16x16x32_bf16 v[18:21], v[166:169], v[182:185], v[18:21]
	v_mfma_f32_16x16x32_bf16 v[14:17], v[170:173], v[182:185], v[14:17]
	v_mfma_f32_16x16x32_bf16 v[10:13], v[174:177], v[182:185], v[10:13]
	v_mfma_f32_16x16x32_bf16 v[6:9], v[178:181], v[182:185], v[6:9]
	v_mfma_f32_16x16x32_bf16 v[62:65], v[142:145], v[186:189], v[62:65]
	v_mfma_f32_16x16x32_bf16 v[58:61], v[150:153], v[186:189], v[58:61]
	v_mfma_f32_16x16x32_bf16 v[54:57], v[158:161], v[186:189], v[54:57]
	v_mfma_f32_16x16x32_bf16 v[50:53], v[162:165], v[186:189], v[50:53]
	v_mfma_f32_16x16x32_bf16 v[46:49], v[166:169], v[186:189], v[46:49]
	v_mfma_f32_16x16x32_bf16 v[42:45], v[170:173], v[186:189], v[42:45]
	v_mfma_f32_16x16x32_bf16 v[38:41], v[174:177], v[186:189], v[38:41]
	v_mfma_f32_16x16x32_bf16 v[2:5], v[178:181], v[186:189], v[2:5]

; __global__ void __launch_bounds__(NTHR) mega_fwd(Params p) {
;     extern __shared__ __attribute__((aligned(16))) char lds[];
	.amdhsa_kernel _Z8mega_fwd6Params
		.amdhsa_group_segment_fixed_size 0
		.amdhsa_private_segment_fixed_size 0
		.amdhsa_kernarg_size 448
		.amdhsa_user_sgpr_count 2
		.amdhsa_user_sgpr_dispatch_ptr 0
		.amdhsa_user_sgpr_queue_ptr 0
		.amdhsa_user_sgpr_kernarg_segment_ptr 1
		.amdhsa_user_sgpr_dispatch_id 0
		.amdhsa_user_sgpr_kernarg_preload_length 0
		.amdhsa_user_sgpr_kernarg_preload_offset 0
		.amdhsa_user_sgpr_private_segment_size 0
		.amdhsa_uses_dynamic_stack 0
		.amdhsa_enable_private_segment 0
		.amdhsa_system_sgpr_workgroup_id_x 1
		.amdhsa_system_sgpr_workgroup_id_y 0
		.amdhsa_system_sgpr_workgroup_id_z 0
		.amdhsa_system_sgpr_workgroup_info 0
		.amdhsa_system_vgpr_workitem_id 2
		.amdhsa_next_free_vgpr 248
		.amdhsa_next_free_sgpr 98
		.amdhsa_accum_offset 248
		.amdhsa_reserve_vcc 1
		.amdhsa_float_round_mode_32 0
		.amdhsa_float_round_mode_16_64 0
		.amdhsa_float_denorm_mode_32 3
		.amdhsa_float_denorm_mode_16_64 3
		.amdhsa_dx10_clamp 1
		.amdhsa_ieee_mode 1
		.amdhsa_fp16_overflow 0
		.amdhsa_tg_split 0
		.amdhsa_exception_fp_ieee_invalid_op 0
		.amdhsa_exception_fp_denorm_src 0
		.amdhsa_exception_fp_ieee_div_zero 0
		.amdhsa_exception_fp_ieee_overflow 0
		.amdhsa_exception_fp_ieee_underflow 0
		.amdhsa_exception_fp_ieee_inexact 0
		.amdhsa_exception_int_div_zero 0
	.end_amdhsa_kernel

amdhsa.kernels:
  - .agpr_count:     0
    .args:
      - .offset:         0
        .size:           192
        .value_kind:     by_value
      - .offset:         192
        .size:           4
        .value_kind:     hidden_block_count_x
      - .offset:         196
        .size:           4
        .value_kind:     hidden_block_count_y
      - .offset:         200
        .size:           4
        .value_kind:     hidden_block_count_z
      - .offset:         204
        .size:           2
        .value_kind:     hidden_group_size_x
      - .offset:         206
        .size:           2
        .value_kind:     hidden_group_size_y
      - .offset:         208
        .size:           2
        .value_kind:     hidden_group_size_z
      - .offset:         210
        .size:           2
        .value_kind:     hidden_remainder_x
      - .offset:         212
        .size:           2
        .value_kind:     hidden_remainder_y
      - .offset:         214
        .size:           2
        .value_kind:     hidden_remainder_z
      - .offset:         232
        .size:           8
        .value_kind:     hidden_global_offset_x
      - .offset:         240
        .size:           8
        .value_kind:     hidden_global_offset_y
      - .offset:         248
        .size:           8
        .value_kind:     hidden_global_offset_z
      - .offset:         256
        .size:           2
        .value_kind:     hidden_grid_dims
      - .offset:         280
        .size:           8
        .value_kind:     hidden_multigrid_sync_arg
      - .offset:         312
        .size:           4
        .value_kind:     hidden_dynamic_lds_size
    .group_segment_fixed_size: 0
    .kernarg_segment_align: 8
    .kernarg_segment_size: 448
    .language:       OpenCL C
    .language_version:
      - 2
      - 0
    .max_flat_workgroup_size: 512
    .name:           _Z8mega_fwd6Params
    .private_segment_fixed_size: 0
    .sgpr_count:     104
    .sgpr_spill_count: 182
    .symbol:         _Z8mega_fwd6Params.kd
    .uniform_work_group_size: 1
    .uses_dynamic_stack: false
    .vgpr_count:     248
    .vgpr_spill_count: 0
    .wavefront_size: 64
